# SCHED re-packed again with class-calibrated item costs (per-item overhead +2us, far segments -3us)
# baseline (speedup 1.0000x reference)
_ZL5SCHED:
	.short	486
	.short	65535
	.short	65535
	.short	488
	.short	65535
	.short	65535
	.short	424
	.short	65535
	.short	65535
	.short	360
	.short	65535
	.short	65535
	.short	422
	.short	65535
	.short	65535
	.short	359
	.short	65535
	.short	65535
	.short	487
	.short	65535
	.short	65535
	.short	423
	.short	65535
	.short	65535
	.short	421
	.short	0
	.short	65535
	.short	420
	.short	385
	.short	65535
	.short	358
	.short	384
	.short	65535
	.short	418
	.short	32
	.short	65535
	.short	355
	.short	66
	.short	65535
	.short	357
	.short	320
	.short	65535
	.short	356
	.short	1
	.short	65535
	.short	483
	.short	386
	.short	65535
	.short	419
	.short	450
	.short	65535
	.short	485
	.short	64
	.short	65535
	.short	481
	.short	259
	.short	65535
	.short	354
	.short	17
	.short	65535
	.short	484
	.short	449
	.short	65535
	.short	482
	.short	41
	.short	65535
	.short	417
	.short	323
	.short	65535
	.short	353
	.short	52
	.short	65535
	.short	453
	.short	1406
	.short	65535
	.short	476
	.short	143
	.short	65535
	.short	313
	.short	262
	.short	65535
	.short	200
	.short	1464
	.short	65535
	.short	316
	.short	327
	.short	65535
	.short	303
	.short	135
	.short	65535
	.short	296
	.short	190
	.short	65535
	.short	311
	.short	391
	.short	65535
	.short	315
	.short	141
	.short	65535
	.short	416
	.short	111
	.short	65535
	.short	478
	.short	121
	.short	65535
	.short	157
	.short	1530
	.short	65535
	.short	312
	.short	159
	.short	65535
	.short	415
	.short	83
	.short	65535
	.short	295
	.short	142
	.short	65535
	.short	959
	.short	156
	.short	65535
	.short	304
	.short	390
	.short	65535
	.short	174
	.short	1529
	.short	65535
	.short	319
	.short	183
	.short	65535
	.short	888
	.short	202
	.short	65535
	.short	1023
	.short	175
	.short	65535
	.short	457
	.short	1527
	.short	65535
	.short	306
	.short	177
	.short	65535
	.short	293
	.short	151
	.short	65535
	.short	350
	.short	119
	.short	65535
	.short	348
	.short	158
	.short	65535
	.short	480
	.short	101
	.short	65535
	.short	78
	.short	1469
	.short	65535
	.short	314
	.short	261
	.short	65535
	.short	299
	.short	186
	.short	65535
	.short	308
	.short	148
	.short	65535
	.short	309
	.short	133
	.short	65535
	.short	297
	.short	144
	.short	65535
	.short	169
	.short	1532
	.short	65535
	.short	301
	.short	164
	.short	65535
	.short	302
	.short	146
	.short	65535
	.short	289
	.short	178
	.short	65535
	.short	292
	.short	325
	.short	65535
	.short	287
	.short	150
	.short	65535
	.short	352
	.short	132
	.short	65535
	.short	477
	.short	160
	.short	65535
	.short	955
	.short	264
	.short	65535
	.short	347
	.short	456
	.short	65535
	.short	285
	.short	167
	.short	65535
	.short	351
	.short	99
	.short	65535
	.short	291
	.short	134
	.short	65535
	.short	170
	.short	1405
	.short	65535
	.short	139
	.short	1465
	.short	65535
	.short	300
	.short	263
	.short	65535
	.short	284
	.short	191
	.short	65535
	.short	90
	.short	1534
	.short	65535
	.short	957
	.short	179
	.short	65535
	.short	307
	.short	163
	.short	65535
	.short	1019
	.short	328
	.short	65535
	.short	89
	.short	1535
	.short	65535
	.short	305
	.short	173
	.short	65535
	.short	394
	.short	1526
	.short	65535
	.short	310
	.short	171
	.short	65535
	.short	180
	.short	1468
	.short	65535
	.short	1021
	.short	153
	.short	65535
	.short	475
	.short	67
	.short	27
	.short	298
	.short	326
	.short	65535
	.short	345
	.short	81
	.short	57
	.short	1015
	.short	97
	.short	62
	.short	282
	.short	88
	.short	2
	.short	889
	.short	195
	.short	35
	.short	882
	.short	117
	.short	123
	.short	891
	.short	324
	.short	42
	.short	10
	.short	56
	.short	1401
	.short	113
	.short	387
	.short	1458
	.short	883
	.short	82
	.short	68
	.short	145
	.short	1467
	.short	65535
	.short	288
	.short	454
	.short	65535
	.short	318
	.short	455
	.short	65535
	.short	184
	.short	1466
	.short	65535
	.short	124
	.short	1533
	.short	65535
	.short	286
	.short	199
	.short	65535
	.short	953
	.short	458
	.short	65535
	.short	147
	.short	1402
	.short	65535
	.short	126
	.short	1470
	.short	65535
	.short	414
	.short	127
	.short	65535
	.short	108
	.short	1471
	.short	65535
	.short	1020
	.short	185
	.short	65535
	.short	290
	.short	198
	.short	65535
	.short	412
	.short	165
	.short	65535
	.short	149
	.short	1404
	.short	65535
	.short	103
	.short	1407
	.short	65535
	.short	958
	.short	176
	.short	65535
	.short	1022
	.short	137
	.short	65535
	.short	954
	.short	393
	.short	65535
	.short	181
	.short	1403
	.short	65535
	.short	294
	.short	161
	.short	65535
	.short	479
	.short	100
	.short	65535
	.short	136
	.short	1531
	.short	65535
	.short	956
	.short	152
	.short	65535
	.short	413
	.short	140
	.short	65535
	.short	890
	.short	265
	.short	65535
	.short	329
	.short	1400
	.short	65535
	.short	317
	.short	197
	.short	65535
	.short	392
	.short	1528
	.short	65535
	.short	349
	.short	389
	.short	65535
	.short	118
	.short	29
	.short	1460
	.short	92
	.short	258
	.short	1399
	.short	1016
	.short	74
	.short	18
	.short	155
	.short	37
	.short	1519
	.short	283
	.short	45
	.short	40
	.short	1010
	.short	168
	.short	47
	.short	346
	.short	120
	.short	65
	.short	79
	.short	321
	.short	1462
	.short	473
	.short	77
	.short	60
	.short	281
	.short	76
	.short	19
	.short	87
	.short	130
	.short	1525
	.short	114
	.short	54
	.short	1397
	.short	948
	.short	95
	.short	196
	.short	410
	.short	125
	.short	26
	.short	1018
	.short	451
	.short	34
	.short	407
	.short	187
	.short	16
	.short	94
	.short	7
	.short	1398
	.short	71
	.short	59
	.short	1396
	.short	947
	.short	84
	.short	110
	.short	73
	.short	63
	.short	1523
	.short	887
	.short	98
	.short	48
	.short	279
	.short	166
	.short	9
	.short	951
	.short	105
	.short	28
	.short	106
	.short	6
	.short	1524
	.short	1012
	.short	96
	.short	388
	.short	1013
	.short	122
	.short	131
	.short	344
	.short	85
	.short	12
	.short	1017
	.short	452
	.short	3
	.short	950
	.short	104
	.short	15
	.short	895
	.short	172
	.short	129
	.short	1011
	.short	107
	.short	75
	.short	409
	.short	102
	.short	13
	.short	946
	.short	162
	.short	38
	.short	886
	.short	70
	.short	4
	.short	109
	.short	25
	.short	1459
	.short	881
	.short	188
	.short	5
	.short	11
	.short	58
	.short	1463
	.short	72
	.short	322
	.short	1461
	.short	408
	.short	69
	.short	260
	.short	893
	.short	80
	.short	50
	.short	474
	.short	91
	.short	44
	.short	892
	.short	115
	.short	36
	.short	154
	.short	43
	.short	1455
	.short	138
	.short	21
	.short	1393
	.short	1014
	.short	93
	.short	61
	.short	343
	.short	182
	.short	194
	.short	189
	.short	193
	.short	1395
	.short	894
	.short	86
	.short	20
	.short	885
	.short	112
	.short	22
	.short	266
	.short	49
	.short	1386
	.short	339
	.short	459
	.short	46
	.short	939
	.short	203
	.short	31
	.short	952
	.short	116
	.short	33
	.short	268
	.short	1457
	.short	65535
	.short	411
	.short	201
	.short	65535
	.short	397
	.short	1394
	.short	65535
	.short	884
	.short	396
	.short	65535
	.short	207
	.short	1387
	.short	65535
	.short	878
	.short	242
	.short	65535
	.short	332
	.short	1521
	.short	65535
	.short	280
	.short	204
	.short	65535
	.short	331
	.short	1522
	.short	65535
	.short	949
	.short	460
	.short	65535
	.short	269
	.short	1520
	.short	65535
	.short	205
	.short	1456
	.short	65535
	.short	1008
	.short	231
	.short	65535
	.short	472
	.short	461
	.short	65535
	.short	471
	.short	462
	.short	65535
	.short	877
	.short	237
	.short	65535
	.short	206
	.short	1518
	.short	65535
	.short	940
	.short	272
	.short	65535
	.short	879
	.short	250
	.short	65535
	.short	217
	.short	1391
	.short	65535
	.short	941
	.short	399
	.short	65535
	.short	468
	.short	336
	.short	65535
	.short	222
	.short	1388
	.short	65535
	.short	944
	.short	244
	.short	65535
	.short	398
	.short	1392
	.short	65535
	.short	880
	.short	229
	.short	65535
	.short	404
	.short	465
	.short	65535
	.short	340
	.short	211
	.short	65535
	.short	938
	.short	274
	.short	65535
	.short	874
	.short	273
	.short	65535
	.short	469
	.short	236
	.short	65535
	.short	275
	.short	337
	.short	65535
	.short	942
	.short	225
	.short	65535
	.short	405
	.short	239
	.short	65535
	.short	1009
	.short	214
	.short	65535
	.short	276
	.short	335
	.short	65535
	.short	254
	.short	1452
	.short	65535
	.short	235
	.short	1450
	.short	65535
	.short	470
	.short	218
	.short	65535
	.short	208
	.short	1453
	.short	65535
	.short	400
	.short	1449
	.short	65535
	.short	246
	.short	1514
	.short	65535
	.short	277
	.short	248
	.short	65535
	.short	1007
	.short	213
	.short	65535
	.short	342
	.short	270
	.short	65535
	.short	227
	.short	1389
	.short	65535
	.short	1006
	.short	224
	.short	65535
	.short	221
	.short	1390
	.short	65535
	.short	223
	.short	1515
	.short	65535
	.short	334
	.short	1454
	.short	65535
	.short	403
	.short	402
	.short	65535
	.short	245
	.short	1451
	.short	65535
	.short	464
	.short	1513
	.short	65535
	.short	406
	.short	228
	.short	65535
	.short	278
	.short	238
	.short	65535
	.short	945
	.short	253
	.short	65535
	.short	341
	.short	215
	.short	65535
	.short	1002
	.short	466
	.short	65535
	.short	875
	.short	401
	.short	65535
	.short	209
	.short	1517
	.short	65535
	.short	1005
	.short	463
	.short	65535
	.short	249
	.short	1516
	.short	65535
	.short	943
	.short	240
	.short	65535
	.short	876
	.short	271
	.short	65535
	.short	395
	.short	8
	.short	1385
	.short	937
	.short	247
	.short	192
	.short	1001
	.short	212
	.short	256
	.short	467
	.short	333
	.short	257
	.short	1003
	.short	267
	.short	51
	.short	216
	.short	243
	.short	14
	.short	241
	.short	252
	.short	24
	.short	1004
	.short	330
	.short	55
	.short	220
	.short	230
	.short	39
	.short	338
	.short	219
	.short	128
	.short	873
	.short	226
	.short	448
	.short	233
	.short	210
	.short	30
	.short	251
	.short	234
	.short	23
	.short	255
	.short	232
	.short	53
	.size	_ZL5SCHED, 1536

	.type	__hip_cuid_3f0aab64d1338eba,@object
